# select_row: a sign probe before the downward binade scan sends negative-threshold rows straight to the digit phases (skips five scan probes and the bit-31 probe)
# speedup vs baseline: 1.0027x; 1.0027x over previous
; DI void select_row(const float* SC, unsigned* dmask, int b, int t, int lane) {
;     ...
;     unsigned T = 0u; bool hit = false; int startbit = 31;
;     {
;         int cnt; SEL_COUNT(0xBF800000u, cnt);
;         if (cnt < 256) {
; #pragma unroll 1
;             for (unsigned e = 0x7Eu; e >= 0x7Au; --e) {
;                 const unsigned cand = 0x80000000u | (e << 23); SEL_COUNT(cand, cnt);
;                 if (cnt >= 256) { T = cand; startbit = 22; hit = (cnt == 256); break; }
;             }
;         }
;     }
.LBB0_553:
	s_nop 1
	v_add_u32_dpp v1, v1, v1 row_shr:1 row_mask:0xf bank_mask:0xf bound_ctrl:1
	s_nop 1
	v_add_u32_dpp v1, v1, v1 row_shr:2 row_mask:0xf bank_mask:0xf bound_ctrl:1
	s_nop 1
	v_add_u32_dpp v1, v1, v1 row_shr:4 row_mask:0xf bank_mask:0xf bound_ctrl:1
	s_nop 1
	v_add_u32_dpp v1, v1, v1 row_shr:8 row_mask:0xf bank_mask:0xf bound_ctrl:1
	s_nop 1
	v_add_u32_dpp v1, v1, v1 row_bcast:15 row_mask:0xa bank_mask:0xf
	s_nop 1
	v_add_u32_dpp v1, v1, v1 row_bcast:31 row_mask:0xc bank_mask:0xf
	s_nop 0
	v_readlane_b32 s8, v1, 63
	s_cmpk_gt_i32 s8, 0xff
	s_cbranch_scc1 .Lsel_up
	s_mov_b32 s14, 0x7f800000
	s_movk_i32 s80, 100
	s_branch .Lsel_up_loop
.Lsel_scan:
	s_movk_i32 s80, 0x7e
	s_mov_b32 s81, 0.5
	s_branch .LBB0_556

; DI void select_row(const float* SC, unsigned* dmask, int b, int t, int lane) {
;     ...
;     unsigned T = 0u; bool hit = false; int startbit = 31;
;     {
;         int cnt; SEL_COUNT(0xBF800000u, cnt);
;         if (cnt < 256) {
; #pragma unroll 1
;             for (unsigned e = 0x7Eu; e >= 0x7Au; --e) {
;                 const unsigned cand = 0x80000000u | (e << 23); SEL_COUNT(cand, cnt);
;                 if (cnt >= 256) { T = cand; startbit = 22; hit = (cnt == 256); break; }
;             }
;         }
;     }
.Lsel_up_g3:
	s_nop 1
	v_add_u32_dpp v4, v4, v4 row_shr:1 row_mask:0xf bank_mask:0xf bound_ctrl:1
	s_nop 1
	v_add_u32_dpp v4, v4, v4 row_shr:2 row_mask:0xf bank_mask:0xf bound_ctrl:1
	s_nop 1
	v_add_u32_dpp v4, v4, v4 row_shr:4 row_mask:0xf bank_mask:0xf bound_ctrl:1
	s_nop 1
	v_add_u32_dpp v4, v4, v4 row_shr:8 row_mask:0xf bank_mask:0xf bound_ctrl:1
	s_nop 1
	v_add_u32_dpp v4, v4, v4 row_bcast:15 row_mask:0xa bank_mask:0xf
	s_nop 1
	v_add_u32_dpp v4, v4, v4 row_bcast:31 row_mask:0xc bank_mask:0xf
	s_nop 1
	v_readlane_b32 s10, v4, 63
	s_cmpk_eq_i32 s80, 100
	s_cbranch_scc1 .Lsel_sign
	s_cmpk_lt_i32 s10, 0x100
	s_cbranch_scc1 .Lsel7
	s_mov_b32 s14, s66
	s_cmpk_eq_i32 s10, 0x100
	s_cbranch_scc1 .Lsel_up_hit
	s_add_i32 s80, s80, -1
	s_cmp_lg_u32 s80, 0
	s_cbranch_scc1 .Lsel_up_loop
	s_branch .LBB0_570

; DI void select_row(const float* SC, unsigned* dmask, int b, int t, int lane) {
;     ...
;     unsigned T = 0u; bool hit = false; int startbit = 31;
;     {
;         int cnt; SEL_COUNT(0xBF800000u, cnt);
;         if (cnt < 256) {
; #pragma unroll 1
;             for (unsigned e = 0x7Eu; e >= 0x7Au; --e) {
;                 const unsigned cand = 0x80000000u | (e << 23); SEL_COUNT(cand, cnt);
;                 if (cnt >= 256) { T = cand; startbit = 22; hit = (cnt == 256); break; }
;             }
;         }
;     }
;     if (!hit) {
;     ...
;             const unsigned cand = T | (1u << bit); int cnt; SEL_COUNT(cand, cnt);
;             if (cnt >= 256) { T = cand; if (cnt == 256) { hit = true; break; } }
;         }
;     }
.Lsel_sign:
	s_cmpk_lt_i32 s10, 0x100
	s_cbranch_scc1 .Lsel_gneg
	s_cmpk_eq_i32 s10, 0x100
	s_cbranch_scc0 .Lsel_scan
	s_mov_b32 s14, s66
	v_mov_b32_e32 v2, s14
	s_mov_b64 s[8:9], -1
	s_branch .LBB0_582
.Lsel_gneg:
	s_mov_b32 s14, 0
	s_mov_b32 s84, 24
	s_branch .Lsel7g
.Lsel_gpos:
	s_mov_b32 s14, 0x80000000
	s_mov_b32 s84, 24
	s_branch .Lsel7g
